# scan loops: batched LDS fragment reads for score and inter MFMA sections (counted lgkmcnt waits), both mLSTM and SSD
# speedup vs baseline: 1.1300x; 1.1300x over previous
; template <bool ISM>
; __device__ void scan_item(const Params& p, int l, int item, unsigned char* lds) {
;     ...
; #pragma unroll
;         for (int a = 0; a < 8; a += 2) {
;             if (a + 1 <= wid) {
;                 bf16x8 kf[2][4];
; #pragma unroll
;                 for (int h2 = 0; h2 < 2; ++h2)
; #pragma unroll
;                     for (int ksd = 0; ksd < 4; ++ksd) kf[h2][ksd] = *(const bf16x8*)(Ks + (16 * (a + h2) + fr) * LDK + ksd * 32 + fq * 8);
; #pragma unroll
;                 for (int ksd = 0; ksd < 4; ++ksd) { sacc[a] = __builtin_amdgcn_mfma_f32_16x16x32_bf16(kf[0][ksd], qc[ksd], sacc[a], 0, 0, 0);
;                     sacc[a + 1] = __builtin_amdgcn_mfma_f32_16x16x32_bf16(kf[1][ksd], qc[ksd], sacc[a + 1], 0, 0, 0); }
;             } else if (a <= wid) {
;                 bf16x8 kf[4];
; #pragma unroll
;                 for (int ksd = 0; ksd < 4; ++ksd) kf[ksd] = *(const bf16x8*)(Ks + (16 * a + fr) * LDK + ksd * 32 + fq * 8);
; #pragma unroll
;                 for (int ksd = 0; ksd < 4; ++ksd) sacc[a] = __builtin_amdgcn_mfma_f32_16x16x32_bf16(kf[ksd], qc[ksd], sacc[a], 0, 0, 0);
;             }
.LBB0_40:
	v_mov_b32_e32 v115, 0
	s_andn2_b64 vcc, exec, s[34:35]
	v_mov_b32_e32 v114, 0
	v_mov_b32_e32 v113, 0
	v_mov_b32_e32 v112, 0
	s_cbranch_vccnz .LBB0_42
	v_add_u32_e32 v88, v171, v173
	ds_read_b128 v[116:119], v88
	ds_read_b128 v[124:127], v88 offset:64
	ds_read_b128 v[132:135], v88 offset:128
	ds_read_b128 v[140:143], v88 offset:192
	s_waitcnt lgkmcnt(3)
	v_mfma_f32_16x16x32_bf16 v[112:115], v[116:119], v[68:71], 0
	s_waitcnt lgkmcnt(2)
	v_mfma_f32_16x16x32_bf16 v[112:115], v[124:127], v[64:67], v[112:115]
	s_waitcnt lgkmcnt(1)
	v_mfma_f32_16x16x32_bf16 v[112:115], v[132:135], v[60:63], v[112:115]
	s_waitcnt lgkmcnt(0)
	v_mfma_f32_16x16x32_bf16 v[112:115], v[140:143], v[56:59], v[112:115]

; template <bool ISM>
; __device__ void scan_item(const Params& p, int l, int item, unsigned char* lds) {
;     ...
; #pragma unroll
;         for (int a = 0; a < 8; a += 2) {
;             if (a + 1 <= wid) {
;                 bf16x8 kf[2][4];
; #pragma unroll
;                 for (int h2 = 0; h2 < 2; ++h2)
; #pragma unroll
;                     for (int ksd = 0; ksd < 4; ++ksd) kf[h2][ksd] = *(const bf16x8*)(Ks + (16 * (a + h2) + fr) * LDK + ksd * 32 + fq * 8);
; #pragma unroll
;                 for (int ksd = 0; ksd < 4; ++ksd) { sacc[a] = __builtin_amdgcn_mfma_f32_16x16x32_bf16(kf[0][ksd], qc[ksd], sacc[a], 0, 0, 0);
;                     sacc[a + 1] = __builtin_amdgcn_mfma_f32_16x16x32_bf16(kf[1][ksd], qc[ksd], sacc[a + 1], 0, 0, 0); }
;             } else if (a <= wid) {
;                 bf16x8 kf[4];
; #pragma unroll
;                 for (int ksd = 0; ksd < 4; ++ksd) kf[ksd] = *(const bf16x8*)(Ks + (16 * a + fr) * LDK + ksd * 32 + fq * 8);
; #pragma unroll
;                 for (int ksd = 0; ksd < 4; ++ksd) sacc[a] = __builtin_amdgcn_mfma_f32_16x16x32_bf16(kf[ksd], qc[ksd], sacc[a], 0, 0, 0);
;             }
.LBB0_43:
	v_mov_b32_e32 v104, 0
	s_andn2_b64 vcc, exec, s[18:19]
	v_add_u32_e32 v92, v171, v173
	v_mov_b32_e32 v105, 0
	v_mov_b32_e32 v106, 0
	v_mov_b32_e32 v107, 0
	s_cbranch_vccnz .LBB0_45
	ds_read_b128 v[116:119], v92
	ds_read_b128 v[120:123], v92 offset:4352
	ds_read_b128 v[124:127], v92 offset:64
	ds_read_b128 v[128:131], v92 offset:4416
	ds_read_b128 v[132:135], v92 offset:128
	ds_read_b128 v[136:139], v92 offset:4480
	ds_read_b128 v[140:143], v92 offset:192
	ds_read_b128 v[232:235], v92 offset:4544
	s_waitcnt lgkmcnt(6)
	v_mfma_f32_16x16x32_bf16 v[112:115], v[116:119], v[68:71], 0
	v_mfma_f32_16x16x32_bf16 v[104:107], v[120:123], v[68:71], 0
	s_waitcnt lgkmcnt(4)
	v_mfma_f32_16x16x32_bf16 v[112:115], v[124:127], v[64:67], v[112:115]
	v_mfma_f32_16x16x32_bf16 v[104:107], v[128:131], v[64:67], v[104:107]
	s_waitcnt lgkmcnt(2)
	v_mfma_f32_16x16x32_bf16 v[112:115], v[132:135], v[60:63], v[112:115]
	v_mfma_f32_16x16x32_bf16 v[104:107], v[136:139], v[60:63], v[104:107]
	s_waitcnt lgkmcnt(0)
	v_mfma_f32_16x16x32_bf16 v[112:115], v[140:143], v[56:59], v[112:115]
	v_mfma_f32_16x16x32_bf16 v[104:107], v[232:235], v[56:59], v[104:107]
.LBB0_45:
	v_cndmask_b32_e64 v80, 0, 1, s[78:79]
	v_cmp_ne_u32_e64 s[28:29], 1, v80
	v_cndmask_b32_e64 v80, 0, 1, s[80:81]
	s_mov_b64 s[18:19], -1
	s_andn2_b64 vcc, exec, s[78:79]
	v_cmp_ne_u32_e64 s[26:27], 1, v80
	s_cbranch_vccnz .LBB0_49
	v_mov_b32_e32 v111, 0
	s_and_b64 vcc, exec, s[26:27]
	v_mov_b32_e32 v110, 0
	v_mov_b32_e32 v109, 0
	v_mov_b32_e32 v108, 0
	s_cbranch_vccnz .LBB0_48
	ds_read_b128 v[116:119], v92 offset:8704
	ds_read_b128 v[124:127], v92 offset:8768
	ds_read_b128 v[132:135], v92 offset:8832
	ds_read_b128 v[140:143], v92 offset:8896
	s_waitcnt lgkmcnt(3)
	v_mfma_f32_16x16x32_bf16 v[108:111], v[116:119], v[68:71], 0
	s_waitcnt lgkmcnt(2)
	v_mfma_f32_16x16x32_bf16 v[108:111], v[124:127], v[64:67], v[108:111]
	s_waitcnt lgkmcnt(1)
	v_mfma_f32_16x16x32_bf16 v[108:111], v[132:135], v[60:63], v[108:111]
	s_waitcnt lgkmcnt(0)
	v_mfma_f32_16x16x32_bf16 v[108:111], v[140:143], v[56:59], v[108:111]

; template <bool ISM>
; __device__ void scan_item(const Params& p, int l, int item, unsigned char* lds) {
;     ...
; #pragma unroll
;         for (int a = 0; a < 8; a += 2) {
;             if (a + 1 <= wid) {
;                 bf16x8 kf[2][4];
; #pragma unroll
;                 for (int h2 = 0; h2 < 2; ++h2)
; #pragma unroll
;                     for (int ksd = 0; ksd < 4; ++ksd) kf[h2][ksd] = *(const bf16x8*)(Ks + (16 * (a + h2) + fr) * LDK + ksd * 32 + fq * 8);
; #pragma unroll
;                 for (int ksd = 0; ksd < 4; ++ksd) { sacc[a] = __builtin_amdgcn_mfma_f32_16x16x32_bf16(kf[0][ksd], qc[ksd], sacc[a], 0, 0, 0);
;                     sacc[a + 1] = __builtin_amdgcn_mfma_f32_16x16x32_bf16(kf[1][ksd], qc[ksd], sacc[a + 1], 0, 0, 0); }
;             } else if (a <= wid) {
;                 bf16x8 kf[4];
; #pragma unroll
;                 for (int ksd = 0; ksd < 4; ++ksd) kf[ksd] = *(const bf16x8*)(Ks + (16 * a + fr) * LDK + ksd * 32 + fq * 8);
; #pragma unroll
;                 for (int ksd = 0; ksd < 4; ++ksd) sacc[a] = __builtin_amdgcn_mfma_f32_16x16x32_bf16(kf[ksd], qc[ksd], sacc[a], 0, 0, 0);
;             }
.LBB0_49:
	v_mov_b32_e32 v96, 0
	s_andn2_b64 vcc, exec, s[18:19]
	v_mov_b32_e32 v97, 0
	v_mov_b32_e32 v98, 0
	v_mov_b32_e32 v99, 0
	s_cbranch_vccnz .LBB0_51
	ds_read_b128 v[116:119], v92 offset:8704
	ds_read_b128 v[120:123], v92 offset:13056
	ds_read_b128 v[124:127], v92 offset:8768
	ds_read_b128 v[128:131], v92 offset:13120
	ds_read_b128 v[132:135], v92 offset:8832
	ds_read_b128 v[136:139], v92 offset:13184
	ds_read_b128 v[140:143], v92 offset:8896
	ds_read_b128 v[232:235], v92 offset:13248
	s_waitcnt lgkmcnt(6)
	v_mfma_f32_16x16x32_bf16 v[108:111], v[116:119], v[68:71], 0
	v_mfma_f32_16x16x32_bf16 v[96:99], v[120:123], v[68:71], 0
	s_waitcnt lgkmcnt(4)
	v_mfma_f32_16x16x32_bf16 v[108:111], v[124:127], v[64:67], v[108:111]
	v_mfma_f32_16x16x32_bf16 v[96:99], v[128:131], v[64:67], v[96:99]
	s_waitcnt lgkmcnt(2)
	v_mfma_f32_16x16x32_bf16 v[108:111], v[132:135], v[60:63], v[108:111]
	v_mfma_f32_16x16x32_bf16 v[96:99], v[136:139], v[60:63], v[96:99]
	s_waitcnt lgkmcnt(0)
	v_mfma_f32_16x16x32_bf16 v[108:111], v[140:143], v[56:59], v[108:111]
	v_mfma_f32_16x16x32_bf16 v[96:99], v[232:235], v[56:59], v[96:99]
.LBB0_51:
	v_cndmask_b32_e64 v80, 0, 1, s[82:83]
	v_cmp_ne_u32_e64 s[24:25], 1, v80
	v_cndmask_b32_e64 v80, 0, 1, s[84:85]
	s_mov_b64 s[18:19], -1
	s_andn2_b64 vcc, exec, s[82:83]
	v_cmp_ne_u32_e64 s[22:23], 1, v80
	s_cbranch_vccnz .LBB0_55
	v_mov_b32_e32 v103, 0
	s_and_b64 vcc, exec, s[22:23]
	v_mov_b32_e32 v102, 0
	v_mov_b32_e32 v101, 0
	v_mov_b32_e32 v100, 0
	s_cbranch_vccnz .LBB0_54
	ds_read_b128 v[116:119], v92 offset:17408
	ds_read_b128 v[124:127], v92 offset:17472
	ds_read_b128 v[132:135], v92 offset:17536
	ds_read_b128 v[140:143], v92 offset:17600
	s_waitcnt lgkmcnt(3)
	v_mfma_f32_16x16x32_bf16 v[100:103], v[116:119], v[68:71], 0
	s_waitcnt lgkmcnt(2)
	v_mfma_f32_16x16x32_bf16 v[100:103], v[124:127], v[64:67], v[100:103]
	s_waitcnt lgkmcnt(1)
	v_mfma_f32_16x16x32_bf16 v[100:103], v[132:135], v[60:63], v[100:103]
	s_waitcnt lgkmcnt(0)
	v_mfma_f32_16x16x32_bf16 v[100:103], v[140:143], v[56:59], v[100:103]

; template <bool ISM>
; __device__ void scan_item(const Params& p, int l, int item, unsigned char* lds) {
;     ...
; #pragma unroll
;         for (int a = 0; a < 8; a += 2) {
;             if (a + 1 <= wid) {
;                 bf16x8 kf[2][4];
; #pragma unroll
;                 for (int h2 = 0; h2 < 2; ++h2)
; #pragma unroll
;                     for (int ksd = 0; ksd < 4; ++ksd) kf[h2][ksd] = *(const bf16x8*)(Ks + (16 * (a + h2) + fr) * LDK + ksd * 32 + fq * 8);
; #pragma unroll
;                 for (int ksd = 0; ksd < 4; ++ksd) { sacc[a] = __builtin_amdgcn_mfma_f32_16x16x32_bf16(kf[0][ksd], qc[ksd], sacc[a], 0, 0, 0);
;                     sacc[a + 1] = __builtin_amdgcn_mfma_f32_16x16x32_bf16(kf[1][ksd], qc[ksd], sacc[a + 1], 0, 0, 0); }
;             } else if (a <= wid) {
;                 bf16x8 kf[4];
; #pragma unroll
;                 for (int ksd = 0; ksd < 4; ++ksd) kf[ksd] = *(const bf16x8*)(Ks + (16 * a + fr) * LDK + ksd * 32 + fq * 8);
; #pragma unroll
;                 for (int ksd = 0; ksd < 4; ++ksd) sacc[a] = __builtin_amdgcn_mfma_f32_16x16x32_bf16(kf[ksd], qc[ksd], sacc[a], 0, 0, 0);
;             }
.LBB0_55:
	v_mov_b32_e32 v84, 0
	s_andn2_b64 vcc, exec, s[18:19]
	v_mov_b32_e32 v85, 0
	v_mov_b32_e32 v86, 0
	v_mov_b32_e32 v87, 0
	s_cbranch_vccnz .LBB0_57
	ds_read_b128 v[116:119], v92 offset:17408
	ds_read_b128 v[120:123], v92 offset:21760
	ds_read_b128 v[124:127], v92 offset:17472
	ds_read_b128 v[128:131], v92 offset:21824
	ds_read_b128 v[132:135], v92 offset:17536
	ds_read_b128 v[136:139], v92 offset:21888
	ds_read_b128 v[140:143], v92 offset:17600
	ds_read_b128 v[232:235], v92 offset:21952
	s_waitcnt lgkmcnt(6)
	v_mfma_f32_16x16x32_bf16 v[100:103], v[116:119], v[68:71], 0
	v_mfma_f32_16x16x32_bf16 v[84:87], v[120:123], v[68:71], 0
	s_waitcnt lgkmcnt(4)
	v_mfma_f32_16x16x32_bf16 v[100:103], v[124:127], v[64:67], v[100:103]
	v_mfma_f32_16x16x32_bf16 v[84:87], v[128:131], v[64:67], v[84:87]
	s_waitcnt lgkmcnt(2)
	v_mfma_f32_16x16x32_bf16 v[100:103], v[132:135], v[60:63], v[100:103]
	v_mfma_f32_16x16x32_bf16 v[84:87], v[136:139], v[60:63], v[84:87]
	s_waitcnt lgkmcnt(0)
	v_mfma_f32_16x16x32_bf16 v[100:103], v[140:143], v[56:59], v[100:103]
	v_mfma_f32_16x16x32_bf16 v[84:87], v[232:235], v[56:59], v[84:87]
.LBB0_57:
	v_cndmask_b32_e64 v80, 0, 1, s[86:87]
	v_cmp_ne_u32_e64 s[20:21], 1, v80
	v_cndmask_b32_e64 v80, 0, 1, s[88:89]
	s_mov_b64 s[38:39], -1
	s_andn2_b64 vcc, exec, s[86:87]
	v_cmp_ne_u32_e64 s[18:19], 1, v80
	s_cbranch_vccnz .LBB0_61
	v_mov_b32_e32 v91, 0
	s_and_b64 vcc, exec, s[18:19]
	v_mov_b32_e32 v90, 0
	v_mov_b32_e32 v89, 0
	v_mov_b32_e32 v88, 0
	s_cbranch_vccnz .LBB0_60
	ds_read_b128 v[116:119], v92 offset:26112
	ds_read_b128 v[124:127], v92 offset:26176
	ds_read_b128 v[132:135], v92 offset:26240
	ds_read_b128 v[140:143], v92 offset:26304
	s_waitcnt lgkmcnt(3)
	v_mfma_f32_16x16x32_bf16 v[88:91], v[116:119], v[68:71], 0
	s_waitcnt lgkmcnt(2)
	v_mfma_f32_16x16x32_bf16 v[88:91], v[124:127], v[64:67], v[88:91]
	s_waitcnt lgkmcnt(1)
	v_mfma_f32_16x16x32_bf16 v[88:91], v[132:135], v[60:63], v[88:91]
	s_waitcnt lgkmcnt(0)
	v_mfma_f32_16x16x32_bf16 v[88:91], v[140:143], v[56:59], v[88:91]

; template <bool ISM>
; __device__ void scan_item(const Params& p, int l, int item, unsigned char* lds) {
;     ...
; #pragma unroll
;         for (int a = 0; a < 8; a += 2) {
;             if (a + 1 <= wid) {
;                 bf16x8 kf[2][4];
; #pragma unroll
;                 for (int h2 = 0; h2 < 2; ++h2)
; #pragma unroll
;                     for (int ksd = 0; ksd < 4; ++ksd) kf[h2][ksd] = *(const bf16x8*)(Ks + (16 * (a + h2) + fr) * LDK + ksd * 32 + fq * 8);
; #pragma unroll
;                 for (int ksd = 0; ksd < 4; ++ksd) { sacc[a] = __builtin_amdgcn_mfma_f32_16x16x32_bf16(kf[0][ksd], qc[ksd], sacc[a], 0, 0, 0);
;                     sacc[a + 1] = __builtin_amdgcn_mfma_f32_16x16x32_bf16(kf[1][ksd], qc[ksd], sacc[a + 1], 0, 0, 0); }
;             } else if (a <= wid) {
;                 bf16x8 kf[4];
; #pragma unroll
;                 for (int ksd = 0; ksd < 4; ++ksd) kf[ksd] = *(const bf16x8*)(Ks + (16 * a + fr) * LDK + ksd * 32 + fq * 8);
; #pragma unroll
;                 for (int ksd = 0; ksd < 4; ++ksd) sacc[a] = __builtin_amdgcn_mfma_f32_16x16x32_bf16(kf[ksd], qc[ksd], sacc[a], 0, 0, 0);
;             }
.LBB0_61:
	s_nop 3
	v_mov_b32_e32 v80, 0
	s_andn2_b64 vcc, exec, s[38:39]
	v_mov_b32_e32 v81, 0
	v_mov_b32_e32 v82, 0
	v_mov_b32_e32 v83, 0
	s_cbranch_vccnz .LBB0_63
	ds_read_b128 v[116:119], v92 offset:26112
	ds_read_b128 v[120:123], v92 offset:30464
	ds_read_b128 v[124:127], v92 offset:26176
	ds_read_b128 v[128:131], v92 offset:30528
	ds_read_b128 v[132:135], v92 offset:26240
	ds_read_b128 v[136:139], v92 offset:30592
	ds_read_b128 v[140:143], v92 offset:26304
	ds_read_b128 v[232:235], v92 offset:30656
	s_waitcnt lgkmcnt(6)
	v_mfma_f32_16x16x32_bf16 v[88:91], v[116:119], v[68:71], 0
	v_mfma_f32_16x16x32_bf16 v[80:83], v[120:123], v[68:71], 0
	s_waitcnt lgkmcnt(4)
	v_mfma_f32_16x16x32_bf16 v[88:91], v[124:127], v[64:67], v[88:91]
	v_mfma_f32_16x16x32_bf16 v[80:83], v[128:131], v[64:67], v[80:83]
	s_waitcnt lgkmcnt(2)
	v_mfma_f32_16x16x32_bf16 v[88:91], v[132:135], v[60:63], v[88:91]
	v_mfma_f32_16x16x32_bf16 v[80:83], v[136:139], v[60:63], v[80:83]
	s_waitcnt lgkmcnt(0)
	v_mfma_f32_16x16x32_bf16 v[88:91], v[140:143], v[56:59], v[88:91]
	v_mfma_f32_16x16x32_bf16 v[80:83], v[232:235], v[56:59], v[80:83]

; __device__ __forceinline__ float bflo(unsigned w) { return __uint_as_float(w << 16); }
; __device__ __forceinline__ float bfhi(unsigned w) { return __uint_as_float(w & 0xFFFF0000u); }
; __device__ __forceinline__ unsigned pk2(float lo, float hi) { const f32x2_t v = {lo, hi}; return __builtin_bit_cast(unsigned, __builtin_convertvector(v, bf16x2_t)); }
; template <bool ISM>
; __device__ void scan_item(const Params& p, int l, int item, unsigned char* lds) {
;     ...
; #pragma unroll
;           for (int rep = 0; rep < 2; ++rep) { const int idx = rep * 512 + tid; const int i = idx >> 3; const float wv = f_ws[i]; const u32x4 vc = rep ? vc1 : vc0; u32x4 o;
; #pragma unroll
;               for (int e = 0; e < 4; ++e) o[e] = pk2(bflo(vc[e]) * wv, bfhi(vc[e]) * wv);
;               *(u32x4*)(Vw + i * LDV + (idx & 7) * 8) = o; }
;           if (ISM && tid < 128) Vw[tid * LDV + 64] = f2bf(f_ws[tid]); }
;         { f32x4 ia[NT], ib[4];
; #pragma unroll
;           for (int n = 0; n < NT; ++n) ia[n] = (f32x4){0.f, 0.f, 0.f, 0.f};
; #pragma unroll
;           for (int n = 0; n < 4; ++n) ib[n] = (f32x4){0.f, 0.f, 0.f, 0.f};
; #pragma unroll
;           for (int ksd = 0; ksd < 4; ++ksd) { bf16x8 bfr[NT];
; #pragma unroll
;               for (int n = 0; n < NT; ++n) bfr[n] = *(const bf16x8*)(CT + (n * 16 + fr) * LDK + ksd * 32 + fq * 8);
; #pragma unroll
;               for (int n = 0; n < NT; ++n) ia[n] = __builtin_amdgcn_mfma_f32_16x16x32_bf16(qc[ksd], bfr[n], ia[n], 0, 0, 0); }
;     ...
;           SCAN_IB(0) SCAN_IB(1) SCAN_IB(2) SCAN_IB(3)
.LBB0_111:
	ds_read_b32 v80, v175
	v_lshlrev_b32_e32 v82, 16, v76
	v_and_b32_e32 v83, 0xffff0000, v76
	v_lshlrev_b32_e32 v84, 16, v77
	v_and_b32_e32 v85, 0xffff0000, v77
	s_waitcnt lgkmcnt(0)
	v_pk_mul_f32 v[76:77], v[80:81], v[82:83] op_sel_hi:[0,1]
	v_pk_mul_f32 v[82:83], v[80:81], v[84:85] op_sel_hi:[0,1]
	v_cvt_pk_bf16_f32 v76, v76, v77
	v_cvt_pk_bf16_f32 v77, v82, v83
	v_lshlrev_b32_e32 v82, 16, v78
	v_and_b32_e32 v83, 0xffff0000, v78
	v_pk_mul_f32 v[82:83], v[80:81], v[82:83] op_sel_hi:[0,1]
	v_cvt_pk_bf16_f32 v78, v82, v83
	v_lshlrev_b32_e32 v82, 16, v79
	v_and_b32_e32 v83, 0xffff0000, v79
	v_pk_mul_f32 v[80:81], v[80:81], v[82:83] op_sel_hi:[0,1]
	v_cvt_pk_bf16_f32 v79, v80, v81
	ds_write_b128 v205, v[76:79] offset:57344
	ds_read_b32 v76, v177
	v_lshlrev_b32_e32 v78, 16, v72
	v_and_b32_e32 v79, 0xffff0000, v72
	s_andn2_b64 vcc, exec, s[34:35]
	s_waitcnt lgkmcnt(0)
	v_pk_mul_f32 v[78:79], v[76:77], v[78:79] op_sel_hi:[0,1]
	v_cvt_pk_bf16_f32 v72, v78, v79
	v_lshlrev_b32_e32 v78, 16, v73
	v_and_b32_e32 v79, 0xffff0000, v73
	v_pk_mul_f32 v[78:79], v[76:77], v[78:79] op_sel_hi:[0,1]
	v_cvt_pk_bf16_f32 v73, v78, v79
	v_lshlrev_b32_e32 v78, 16, v74
	v_and_b32_e32 v79, 0xffff0000, v74
	v_pk_mul_f32 v[78:79], v[76:77], v[78:79] op_sel_hi:[0,1]
	v_cvt_pk_bf16_f32 v74, v78, v79
	v_lshlrev_b32_e32 v78, 16, v75
	v_and_b32_e32 v79, 0xffff0000, v75
	v_pk_mul_f32 v[76:77], v[76:77], v[78:79] op_sel_hi:[0,1]
	v_cvt_pk_bf16_f32 v75, v76, v77
	ds_write_b128 v223, v[72:75] offset:57344
	ds_read_b128 v[72:75], v203
	ds_read_b128 v[76:79], v203 offset:4352
	ds_read_b128 v[80:83], v203 offset:8704
	ds_read_b128 v[84:87], v203 offset:13056
	ds_read_b128 v[124:127], v203 offset:64
	ds_read_b128 v[128:131], v203 offset:4416
	ds_read_b128 v[132:135], v203 offset:8768
	ds_read_b128 v[136:139], v203 offset:13120
	ds_read_b128 v[140:143], v203 offset:128
	ds_read_b128 v[116:119], v203 offset:4480
	ds_read_b128 v[232:235], v203 offset:8832
	ds_read_b128 v[236:239], v203 offset:13184
	s_waitcnt lgkmcnt(11)
	v_mfma_f32_16x16x32_bf16 v[72:75], v[68:71], v[72:75], 0
	s_waitcnt lgkmcnt(10)
	v_mfma_f32_16x16x32_bf16 v[76:79], v[68:71], v[76:79], 0
	s_waitcnt lgkmcnt(9)
	v_mfma_f32_16x16x32_bf16 v[80:83], v[68:71], v[80:83], 0
	s_waitcnt lgkmcnt(8)
	v_mfma_f32_16x16x32_bf16 v[84:87], v[68:71], v[84:87], 0
	ds_read_b128 v[240:243], v203 offset:192
	ds_read_b128 v[244:247], v203 offset:4544
	ds_read_b128 v[248:251], v203 offset:8896
	ds_read_b128 v[92:95], v203 offset:13248
	s_waitcnt lgkmcnt(11)
	v_mfma_f32_16x16x32_bf16 v[72:75], v[64:67], v[124:127], v[72:75]
	s_waitcnt lgkmcnt(10)
	v_mfma_f32_16x16x32_bf16 v[76:79], v[64:67], v[128:131], v[76:79]
	s_waitcnt lgkmcnt(9)
	v_mfma_f32_16x16x32_bf16 v[80:83], v[64:67], v[132:135], v[80:83]
	s_waitcnt lgkmcnt(8)
	v_mfma_f32_16x16x32_bf16 v[84:87], v[64:67], v[136:139], v[84:87]
	s_waitcnt lgkmcnt(7)
	v_mfma_f32_16x16x32_bf16 v[72:75], v[60:63], v[140:143], v[72:75]
	s_waitcnt lgkmcnt(6)
	v_mfma_f32_16x16x32_bf16 v[76:79], v[60:63], v[116:119], v[76:79]
	s_waitcnt lgkmcnt(5)
	v_mfma_f32_16x16x32_bf16 v[80:83], v[60:63], v[232:235], v[80:83]
	s_waitcnt lgkmcnt(4)
	v_mfma_f32_16x16x32_bf16 v[84:87], v[60:63], v[236:239], v[84:87]
	s_waitcnt lgkmcnt(3)
	v_mfma_f32_16x16x32_bf16 v[60:63], v[56:59], v[240:243], v[72:75]
	s_waitcnt lgkmcnt(2)
	v_mfma_f32_16x16x32_bf16 v[64:67], v[56:59], v[244:247], v[76:79]
	s_waitcnt lgkmcnt(1)
	v_mfma_f32_16x16x32_bf16 v[80:83], v[56:59], v[248:251], v[80:83]
	s_waitcnt lgkmcnt(0)
	v_mfma_f32_16x16x32_bf16 v[56:59], v[56:59], v[92:95], v[84:87]
	s_cbranch_vccnz .LBB0_150
	s_nop 1
	v_cvt_pk_bf16_f32 v84, v148, v193
	v_cvt_pk_bf16_f32 v85, v195, v197
	v_cvt_pk_bf16_f32 v86, v112, v113
	v_cvt_pk_bf16_f32 v87, v114, v115
	ds_read_b64_tr_b16 v[68:69], v159 offset:0
	ds_read_b64_tr_b16 v[70:71], v159 offset:0xb00
	ds_read_b64_tr_b16 v[72:73], v159 offset:32
	ds_read_b64_tr_b16 v[74:75], v159 offset:0xb20
	ds_read_b64_tr_b16 v[76:77], v159 offset:64
	ds_read_b64_tr_b16 v[78:79], v159 offset:0xb40
	ds_read_b64_tr_b16 v[92:93], v159 offset:0x60
	ds_read_b64_tr_b16 v[94:95], v159 offset:0xb60
	s_waitcnt lgkmcnt(0)
	s_nop 1
	v_mfma_f32_16x16x32_bf16 v[68:71], v[84:87], v[68:71], 0
	v_mfma_f32_16x16x32_bf16 v[72:75], v[84:87], v[72:75], 0
	v_mfma_f32_16x16x32_bf16 v[76:79], v[84:87], v[76:79], 0
	v_mfma_f32_16x16x32_bf16 v[84:87], v[84:87], v[92:95], 0
	s_andn2_b64 vcc, exec, s[42:43]
	s_cbranch_vccnz .LBB0_114

; template <bool ISM>
; __device__ void scan_item(const Params& p, int l, int item, unsigned char* lds) {
;     ...
; #pragma unroll
;         for (int a = 0; a < 8; a += 2) {
;             if (a + 1 <= wid) {
;                 bf16x8 kf[2][4];
; #pragma unroll
;                 for (int h2 = 0; h2 < 2; ++h2)
; #pragma unroll
;                     for (int ksd = 0; ksd < 4; ++ksd) kf[h2][ksd] = *(const bf16x8*)(Ks + (16 * (a + h2) + fr) * LDK + ksd * 32 + fq * 8);
; #pragma unroll
;                 for (int ksd = 0; ksd < 4; ++ksd) { sacc[a] = __builtin_amdgcn_mfma_f32_16x16x32_bf16(kf[0][ksd], qc[ksd], sacc[a], 0, 0, 0);
;                     sacc[a + 1] = __builtin_amdgcn_mfma_f32_16x16x32_bf16(kf[1][ksd], qc[ksd], sacc[a + 1], 0, 0, 0); }
;             } else if (a <= wid) {
;                 bf16x8 kf[4];
; #pragma unroll
;                 for (int ksd = 0; ksd < 4; ++ksd) kf[ksd] = *(const bf16x8*)(Ks + (16 * a + fr) * LDK + ksd * 32 + fq * 8);
; #pragma unroll
;                 for (int ksd = 0; ksd < 4; ++ksd) sacc[a] = __builtin_amdgcn_mfma_f32_16x16x32_bf16(kf[ksd], qc[ksd], sacc[a], 0, 0, 0);
;             }
.LBB0_172:
	v_mov_b32_e32 v127, 0
	s_andn2_b64 vcc, exec, s[76:77]
	v_mov_b32_e32 v126, 0
	v_mov_b32_e32 v125, 0
	v_mov_b32_e32 v124, 0
	s_cbranch_vccnz .LBB0_174
	v_add_u32_e32 v92, v225, v175
	ds_read_b128 v[120:123], v92
	ds_read_b128 v[132:135], v92 offset:64
	ds_read_b128 v[140:143], v92 offset:128
	ds_read_b128 v[108:111], v92 offset:192
	s_waitcnt lgkmcnt(3)
	v_mfma_f32_16x16x32_bf16 v[124:127], v[120:123], v[72:75], 0
	s_waitcnt lgkmcnt(2)
	v_mfma_f32_16x16x32_bf16 v[124:127], v[132:135], v[68:71], v[124:127]
	s_waitcnt lgkmcnt(1)
	v_mfma_f32_16x16x32_bf16 v[124:127], v[140:143], v[64:67], v[124:127]
	s_waitcnt lgkmcnt(0)
	v_mfma_f32_16x16x32_bf16 v[124:127], v[108:111], v[60:63], v[124:127]

; template <bool ISM>
; __device__ void scan_item(const Params& p, int l, int item, unsigned char* lds) {
;     ...
; #pragma unroll
;         for (int a = 0; a < 8; a += 2) {
;             if (a + 1 <= wid) {
;                 bf16x8 kf[2][4];
; #pragma unroll
;                 for (int h2 = 0; h2 < 2; ++h2)
; #pragma unroll
;                     for (int ksd = 0; ksd < 4; ++ksd) kf[h2][ksd] = *(const bf16x8*)(Ks + (16 * (a + h2) + fr) * LDK + ksd * 32 + fq * 8);
; #pragma unroll
;                 for (int ksd = 0; ksd < 4; ++ksd) { sacc[a] = __builtin_amdgcn_mfma_f32_16x16x32_bf16(kf[0][ksd], qc[ksd], sacc[a], 0, 0, 0);
;                     sacc[a + 1] = __builtin_amdgcn_mfma_f32_16x16x32_bf16(kf[1][ksd], qc[ksd], sacc[a + 1], 0, 0, 0); }
;             } else if (a <= wid) {
;                 bf16x8 kf[4];
; #pragma unroll
;                 for (int ksd = 0; ksd < 4; ++ksd) kf[ksd] = *(const bf16x8*)(Ks + (16 * a + fr) * LDK + ksd * 32 + fq * 8);
; #pragma unroll
;                 for (int ksd = 0; ksd < 4; ++ksd) sacc[a] = __builtin_amdgcn_mfma_f32_16x16x32_bf16(kf[ksd], qc[ksd], sacc[a], 0, 0, 0);
;             }
.LBB0_175:
	v_mov_b32_e32 v116, 0
	s_andn2_b64 vcc, exec, s[4:5]
	v_add_u32_e32 v88, v225, v175
	v_mov_b32_e32 v117, 0
	v_mov_b32_e32 v118, 0
	v_mov_b32_e32 v119, 0
	s_cbranch_vccnz .LBB0_177
	ds_read_b128 v[120:123], v88
	ds_read_b128 v[128:131], v88 offset:4352
	ds_read_b128 v[132:135], v88 offset:64
	ds_read_b128 v[136:139], v88 offset:4416
	ds_read_b128 v[140:143], v88 offset:128
	ds_read_b128 v[144:147], v88 offset:4480
	ds_read_b128 v[108:111], v88 offset:192
	ds_read_b128 v[244:247], v88 offset:4544
	s_waitcnt lgkmcnt(6)
	v_mfma_f32_16x16x32_bf16 v[124:127], v[120:123], v[72:75], 0
	v_mfma_f32_16x16x32_bf16 v[116:119], v[128:131], v[72:75], 0
	s_waitcnt lgkmcnt(4)
	v_mfma_f32_16x16x32_bf16 v[124:127], v[132:135], v[68:71], v[124:127]
	v_mfma_f32_16x16x32_bf16 v[116:119], v[136:139], v[68:71], v[116:119]
	s_waitcnt lgkmcnt(2)
	v_mfma_f32_16x16x32_bf16 v[124:127], v[140:143], v[64:67], v[124:127]
	v_mfma_f32_16x16x32_bf16 v[116:119], v[144:147], v[64:67], v[116:119]
	s_waitcnt lgkmcnt(0)
	v_mfma_f32_16x16x32_bf16 v[124:127], v[108:111], v[60:63], v[124:127]
	v_mfma_f32_16x16x32_bf16 v[116:119], v[244:247], v[60:63], v[116:119]
.LBB0_177:
	v_cndmask_b32_e64 v84, 0, 1, s[94:95]
	v_cmp_ne_u32_e64 s[26:27], 1, v84
	v_cndmask_b32_e64 v84, 0, 1, s[96:97]
	s_mov_b64 s[4:5], -1
	s_andn2_b64 vcc, exec, s[94:95]
	v_cmp_ne_u32_e64 s[24:25], 1, v84
	s_cbranch_vccnz .LBB0_181
	v_mov_b32_e32 v115, 0
	s_and_b64 vcc, exec, s[24:25]
	v_mov_b32_e32 v114, 0
	v_mov_b32_e32 v113, 0
	v_mov_b32_e32 v112, 0
	s_cbranch_vccnz .LBB0_180
	ds_read_b128 v[120:123], v88 offset:8704
	ds_read_b128 v[132:135], v88 offset:8768
	ds_read_b128 v[140:143], v88 offset:8832
	ds_read_b128 v[108:111], v88 offset:8896
	s_waitcnt lgkmcnt(3)
	v_mfma_f32_16x16x32_bf16 v[112:115], v[120:123], v[72:75], 0
	s_waitcnt lgkmcnt(2)
	v_mfma_f32_16x16x32_bf16 v[112:115], v[132:135], v[68:71], v[112:115]
	s_waitcnt lgkmcnt(1)
	v_mfma_f32_16x16x32_bf16 v[112:115], v[140:143], v[64:67], v[112:115]
	s_waitcnt lgkmcnt(0)
	v_mfma_f32_16x16x32_bf16 v[112:115], v[108:111], v[60:63], v[112:115]

; template <bool ISM>
; __device__ void scan_item(const Params& p, int l, int item, unsigned char* lds) {
;     ...
; #pragma unroll
;         for (int a = 0; a < 8; a += 2) {
;             if (a + 1 <= wid) {
;                 bf16x8 kf[2][4];
; #pragma unroll
;                 for (int h2 = 0; h2 < 2; ++h2)
; #pragma unroll
;                     for (int ksd = 0; ksd < 4; ++ksd) kf[h2][ksd] = *(const bf16x8*)(Ks + (16 * (a + h2) + fr) * LDK + ksd * 32 + fq * 8);
; #pragma unroll
;                 for (int ksd = 0; ksd < 4; ++ksd) { sacc[a] = __builtin_amdgcn_mfma_f32_16x16x32_bf16(kf[0][ksd], qc[ksd], sacc[a], 0, 0, 0);
;                     sacc[a + 1] = __builtin_amdgcn_mfma_f32_16x16x32_bf16(kf[1][ksd], qc[ksd], sacc[a + 1], 0, 0, 0); }
;             } else if (a <= wid) {
;                 bf16x8 kf[4];
; #pragma unroll
;                 for (int ksd = 0; ksd < 4; ++ksd) kf[ksd] = *(const bf16x8*)(Ks + (16 * a + fr) * LDK + ksd * 32 + fq * 8);
; #pragma unroll
;                 for (int ksd = 0; ksd < 4; ++ksd) sacc[a] = __builtin_amdgcn_mfma_f32_16x16x32_bf16(kf[ksd], qc[ksd], sacc[a], 0, 0, 0);
;             }
.LBB0_181:
	v_mov_b32_e32 v104, 0
	s_andn2_b64 vcc, exec, s[4:5]
	v_mov_b32_e32 v105, 0
	v_mov_b32_e32 v106, 0
	v_mov_b32_e32 v107, 0
	s_cbranch_vccnz .LBB0_183
	ds_read_b128 v[120:123], v88 offset:8704
	ds_read_b128 v[128:131], v88 offset:13056
	ds_read_b128 v[132:135], v88 offset:8768
	ds_read_b128 v[136:139], v88 offset:13120
	ds_read_b128 v[140:143], v88 offset:8832
	ds_read_b128 v[144:147], v88 offset:13184
	ds_read_b128 v[108:111], v88 offset:8896
	ds_read_b128 v[244:247], v88 offset:13248
	s_waitcnt lgkmcnt(6)
	v_mfma_f32_16x16x32_bf16 v[112:115], v[120:123], v[72:75], 0
	v_mfma_f32_16x16x32_bf16 v[104:107], v[128:131], v[72:75], 0
	s_waitcnt lgkmcnt(4)
	v_mfma_f32_16x16x32_bf16 v[112:115], v[132:135], v[68:71], v[112:115]
	v_mfma_f32_16x16x32_bf16 v[104:107], v[136:139], v[68:71], v[104:107]
	s_waitcnt lgkmcnt(2)
	v_mfma_f32_16x16x32_bf16 v[112:115], v[140:143], v[64:67], v[112:115]
	v_mfma_f32_16x16x32_bf16 v[104:107], v[144:147], v[64:67], v[104:107]
	s_waitcnt lgkmcnt(0)
	v_mfma_f32_16x16x32_bf16 v[112:115], v[108:111], v[60:63], v[112:115]
	v_mfma_f32_16x16x32_bf16 v[104:107], v[244:247], v[60:63], v[104:107]
.LBB0_183:
	v_cndmask_b32_e64 v84, 0, 1, s[98:99]
	v_cmp_ne_u32_e64 s[22:23], 1, v84
	v_cndmask_b32_e64 v84, 0, 1, s[48:49]
	s_mov_b64 s[4:5], -1
	s_andn2_b64 vcc, exec, s[98:99]
	v_cmp_ne_u32_e64 s[20:21], 1, v84
	s_cbranch_vccnz .LBB0_187
	v_mov_b32_e32 v103, 0
	s_and_b64 vcc, exec, s[20:21]
	v_mov_b32_e32 v102, 0
	v_mov_b32_e32 v101, 0
	v_mov_b32_e32 v100, 0
	s_cbranch_vccnz .LBB0_186
	ds_read_b128 v[120:123], v88 offset:17408
	ds_read_b128 v[132:135], v88 offset:17472
	ds_read_b128 v[140:143], v88 offset:17536
	ds_read_b128 v[108:111], v88 offset:17600
	s_waitcnt lgkmcnt(3)
	v_mfma_f32_16x16x32_bf16 v[100:103], v[120:123], v[72:75], 0
	s_waitcnt lgkmcnt(2)
	v_mfma_f32_16x16x32_bf16 v[100:103], v[132:135], v[68:71], v[100:103]
	s_waitcnt lgkmcnt(1)
	v_mfma_f32_16x16x32_bf16 v[100:103], v[140:143], v[64:67], v[100:103]
	s_waitcnt lgkmcnt(0)
	v_mfma_f32_16x16x32_bf16 v[100:103], v[108:111], v[60:63], v[100:103]

; template <bool ISM>
; __device__ void scan_item(const Params& p, int l, int item, unsigned char* lds) {
;     ...
; #pragma unroll
;         for (int a = 0; a < 8; a += 2) {
;             if (a + 1 <= wid) {
;                 bf16x8 kf[2][4];
; #pragma unroll
;                 for (int h2 = 0; h2 < 2; ++h2)
; #pragma unroll
;                     for (int ksd = 0; ksd < 4; ++ksd) kf[h2][ksd] = *(const bf16x8*)(Ks + (16 * (a + h2) + fr) * LDK + ksd * 32 + fq * 8);
; #pragma unroll
;                 for (int ksd = 0; ksd < 4; ++ksd) { sacc[a] = __builtin_amdgcn_mfma_f32_16x16x32_bf16(kf[0][ksd], qc[ksd], sacc[a], 0, 0, 0);
;                     sacc[a + 1] = __builtin_amdgcn_mfma_f32_16x16x32_bf16(kf[1][ksd], qc[ksd], sacc[a + 1], 0, 0, 0); }
;             } else if (a <= wid) {
;                 bf16x8 kf[4];
; #pragma unroll
;                 for (int ksd = 0; ksd < 4; ++ksd) kf[ksd] = *(const bf16x8*)(Ks + (16 * a + fr) * LDK + ksd * 32 + fq * 8);
; #pragma unroll
;                 for (int ksd = 0; ksd < 4; ++ksd) sacc[a] = __builtin_amdgcn_mfma_f32_16x16x32_bf16(kf[ksd], qc[ksd], sacc[a], 0, 0, 0);
;             }
.LBB0_187:
	v_mov_b32_e32 v96, 0
	s_andn2_b64 vcc, exec, s[4:5]
	v_mov_b32_e32 v97, 0
	v_mov_b32_e32 v98, 0
	v_mov_b32_e32 v99, 0
	s_cbranch_vccnz .LBB0_189
	ds_read_b128 v[120:123], v88 offset:17408
	ds_read_b128 v[128:131], v88 offset:21760
	ds_read_b128 v[132:135], v88 offset:17472
	ds_read_b128 v[136:139], v88 offset:21824
	ds_read_b128 v[140:143], v88 offset:17536
	ds_read_b128 v[144:147], v88 offset:21888
	ds_read_b128 v[108:111], v88 offset:17600
	ds_read_b128 v[244:247], v88 offset:21952
	s_waitcnt lgkmcnt(6)
	v_mfma_f32_16x16x32_bf16 v[100:103], v[120:123], v[72:75], 0
	v_mfma_f32_16x16x32_bf16 v[96:99], v[128:131], v[72:75], 0
	s_waitcnt lgkmcnt(4)
	v_mfma_f32_16x16x32_bf16 v[100:103], v[132:135], v[68:71], v[100:103]
	v_mfma_f32_16x16x32_bf16 v[96:99], v[136:139], v[68:71], v[96:99]
	s_waitcnt lgkmcnt(2)
	v_mfma_f32_16x16x32_bf16 v[100:103], v[140:143], v[64:67], v[100:103]
	v_mfma_f32_16x16x32_bf16 v[96:99], v[144:147], v[64:67], v[96:99]
	s_waitcnt lgkmcnt(0)
	v_mfma_f32_16x16x32_bf16 v[100:103], v[108:111], v[60:63], v[100:103]
	v_mfma_f32_16x16x32_bf16 v[96:99], v[244:247], v[60:63], v[96:99]
.LBB0_189:
	v_cndmask_b32_e64 v84, 0, 1, s[52:53]
	v_cmp_ne_u32_e64 s[18:19], 1, v84
	v_cndmask_b32_e64 v84, 0, 1, s[54:55]
	s_mov_b64 s[4:5], -1
	s_andn2_b64 vcc, exec, s[52:53]
	v_cmp_ne_u32_e64 s[16:17], 1, v84
	s_cbranch_vccnz .LBB0_193
	v_mov_b32_e32 v95, 0
	s_and_b64 vcc, exec, s[16:17]
	v_mov_b32_e32 v94, 0
	v_mov_b32_e32 v93, 0
	v_mov_b32_e32 v92, 0
	s_cbranch_vccnz .LBB0_192
	ds_read_b128 v[120:123], v88 offset:26112
	ds_read_b128 v[132:135], v88 offset:26176
	ds_read_b128 v[140:143], v88 offset:26240
	ds_read_b128 v[108:111], v88 offset:26304
	s_waitcnt lgkmcnt(3)
	v_mfma_f32_16x16x32_bf16 v[92:95], v[120:123], v[72:75], 0
	s_waitcnt lgkmcnt(2)
	v_mfma_f32_16x16x32_bf16 v[92:95], v[132:135], v[68:71], v[92:95]
	s_waitcnt lgkmcnt(1)
	v_mfma_f32_16x16x32_bf16 v[92:95], v[140:143], v[64:67], v[92:95]
	s_waitcnt lgkmcnt(0)
	v_mfma_f32_16x16x32_bf16 v[92:95], v[108:111], v[60:63], v[92:95]

; template <bool ISM>
; __device__ void scan_item(const Params& p, int l, int item, unsigned char* lds) {
;     ...
; #pragma unroll
;         for (int a = 0; a < 8; a += 2) {
;             if (a + 1 <= wid) {
;                 bf16x8 kf[2][4];
; #pragma unroll
;                 for (int h2 = 0; h2 < 2; ++h2)
; #pragma unroll
;                     for (int ksd = 0; ksd < 4; ++ksd) kf[h2][ksd] = *(const bf16x8*)(Ks + (16 * (a + h2) + fr) * LDK + ksd * 32 + fq * 8);
; #pragma unroll
;                 for (int ksd = 0; ksd < 4; ++ksd) { sacc[a] = __builtin_amdgcn_mfma_f32_16x16x32_bf16(kf[0][ksd], qc[ksd], sacc[a], 0, 0, 0);
;                     sacc[a + 1] = __builtin_amdgcn_mfma_f32_16x16x32_bf16(kf[1][ksd], qc[ksd], sacc[a + 1], 0, 0, 0); }
;             } else if (a <= wid) {
;                 bf16x8 kf[4];
; #pragma unroll
;                 for (int ksd = 0; ksd < 4; ++ksd) kf[ksd] = *(const bf16x8*)(Ks + (16 * a + fr) * LDK + ksd * 32 + fq * 8);
; #pragma unroll
;                 for (int ksd = 0; ksd < 4; ++ksd) sacc[a] = __builtin_amdgcn_mfma_f32_16x16x32_bf16(kf[ksd], qc[ksd], sacc[a], 0, 0, 0);
;             }
.LBB0_193:
	s_nop 3
	v_mov_b32_e32 v84, 0
	s_andn2_b64 vcc, exec, s[4:5]
	v_mov_b32_e32 v85, 0
	v_mov_b32_e32 v86, 0
	v_mov_b32_e32 v87, 0
	s_cbranch_vccnz .LBB0_195
	ds_read_b128 v[120:123], v88 offset:26112
	ds_read_b128 v[128:131], v88 offset:30464
	ds_read_b128 v[132:135], v88 offset:26176
	ds_read_b128 v[136:139], v88 offset:30528
	ds_read_b128 v[140:143], v88 offset:26240
	ds_read_b128 v[144:147], v88 offset:30592
	ds_read_b128 v[108:111], v88 offset:26304
	ds_read_b128 v[244:247], v88 offset:30656
	s_waitcnt lgkmcnt(6)
	v_mfma_f32_16x16x32_bf16 v[92:95], v[120:123], v[72:75], 0
	v_mfma_f32_16x16x32_bf16 v[84:87], v[128:131], v[72:75], 0
	s_waitcnt lgkmcnt(4)
	v_mfma_f32_16x16x32_bf16 v[92:95], v[132:135], v[68:71], v[92:95]
	v_mfma_f32_16x16x32_bf16 v[84:87], v[136:139], v[68:71], v[84:87]
	s_waitcnt lgkmcnt(2)
	v_mfma_f32_16x16x32_bf16 v[92:95], v[140:143], v[64:67], v[92:95]
	v_mfma_f32_16x16x32_bf16 v[84:87], v[144:147], v[64:67], v[84:87]
	s_waitcnt lgkmcnt(0)
	v_mfma_f32_16x16x32_bf16 v[92:95], v[108:111], v[60:63], v[92:95]
	v_mfma_f32_16x16x32_bf16 v[84:87], v[244:247], v[60:63], v[84:87]

; template <bool ISM>
; __device__ void scan_item(const Params& p, int l, int item, unsigned char* lds) {
;     ...
;         { f32x4 ia[NT], ib[4];
; #pragma unroll
;           for (int n = 0; n < NT; ++n) ia[n] = (f32x4){0.f, 0.f, 0.f, 0.f};
; #pragma unroll
;           for (int n = 0; n < 4; ++n) ib[n] = (f32x4){0.f, 0.f, 0.f, 0.f};
; #pragma unroll
;           for (int ksd = 0; ksd < 4; ++ksd) { bf16x8 bfr[NT];
; #pragma unroll
;               for (int n = 0; n < NT; ++n) bfr[n] = *(const bf16x8*)(CT + (n * 16 + fr) * LDK + ksd * 32 + fq * 8);
; #pragma unroll
;               for (int n = 0; n < NT; ++n) ia[n] = __builtin_amdgcn_mfma_f32_16x16x32_bf16(qc[ksd], bfr[n], ia[n], 0, 0, 0); }
;     ...
;           SCAN_IB(0) SCAN_IB(1) SCAN_IB(2) SCAN_IB(3)
.LBB0_238:
	s_or_b64 exec, exec, s[4:5]
	ds_read_b128 v[80:83], v234
	ds_read_b128 v[84:87], v234 offset:4352
	ds_read_b128 v[88:91], v234 offset:8704
	ds_read_b128 v[76:79], v234 offset:13056
	ds_read_b128 v[92:95], v234 offset:17408
	ds_read_b128 v[128:131], v234 offset:64
	ds_read_b128 v[132:135], v234 offset:4416
	ds_read_b128 v[136:139], v234 offset:8768
	ds_read_b128 v[140:143], v234 offset:13120
	ds_read_b128 v[144:147], v234 offset:17472
	ds_read_b128 v[244:247], v234 offset:128
	ds_read_b128 v[248:251], v234 offset:4480
	s_andn2_b64 vcc, exec, s[76:77]
	s_waitcnt lgkmcnt(11)
	v_mfma_f32_16x16x32_bf16 v[80:83], v[72:75], v[80:83], 0
	s_waitcnt lgkmcnt(10)
	v_mfma_f32_16x16x32_bf16 v[84:87], v[72:75], v[84:87], 0
	s_waitcnt lgkmcnt(9)
	v_mfma_f32_16x16x32_bf16 v[88:91], v[72:75], v[88:91], 0
	s_waitcnt lgkmcnt(8)
	v_mfma_f32_16x16x32_bf16 v[76:79], v[72:75], v[76:79], 0
	s_waitcnt lgkmcnt(7)
	v_mfma_f32_16x16x32_bf16 v[92:95], v[72:75], v[92:95], 0
	s_waitcnt lgkmcnt(6)
	v_mfma_f32_16x16x32_bf16 v[80:83], v[68:71], v[128:131], v[80:83]
	ds_read_b128 v[128:131], v234 offset:8832
	s_waitcnt lgkmcnt(6)
	v_mfma_f32_16x16x32_bf16 v[84:87], v[68:71], v[132:135], v[84:87]
	ds_read_b128 v[132:135], v234 offset:13184
	s_waitcnt lgkmcnt(6)
	v_mfma_f32_16x16x32_bf16 v[88:91], v[68:71], v[136:139], v[88:91]
	ds_read_b128 v[136:139], v234 offset:17536
	s_waitcnt lgkmcnt(6)
	v_mfma_f32_16x16x32_bf16 v[76:79], v[68:71], v[140:143], v[76:79]
	ds_read_b128 v[140:143], v234 offset:192
	s_waitcnt lgkmcnt(6)
	v_mfma_f32_16x16x32_bf16 v[92:95], v[68:71], v[144:147], v[92:95]
	ds_read_b128 v[144:147], v234 offset:4544
	s_waitcnt lgkmcnt(6)
	v_mfma_f32_16x16x32_bf16 v[80:83], v[64:67], v[244:247], v[80:83]
	ds_read_b128 v[244:247], v234 offset:8896
	s_waitcnt lgkmcnt(6)
	v_mfma_f32_16x16x32_bf16 v[84:87], v[64:67], v[248:251], v[84:87]
	ds_read_b128 v[248:251], v234 offset:13248
	s_waitcnt lgkmcnt(6)
	v_mfma_f32_16x16x32_bf16 v[88:91], v[64:67], v[128:131], v[88:91]
	ds_read_b128 v[128:131], v234 offset:17600
	s_waitcnt lgkmcnt(6)
	v_mfma_f32_16x16x32_bf16 v[76:79], v[64:67], v[132:135], v[76:79]
	s_waitcnt lgkmcnt(5)
	v_mfma_f32_16x16x32_bf16 v[92:95], v[64:67], v[136:139], v[92:95]
	s_waitcnt lgkmcnt(4)
	v_mfma_f32_16x16x32_bf16 v[64:67], v[60:63], v[140:143], v[80:83]
	s_waitcnt lgkmcnt(3)
	v_mfma_f32_16x16x32_bf16 v[68:71], v[60:63], v[144:147], v[84:87]
	s_waitcnt lgkmcnt(2)
	v_mfma_f32_16x16x32_bf16 v[72:75], v[60:63], v[244:247], v[88:91]
	s_waitcnt lgkmcnt(1)
	v_mfma_f32_16x16x32_bf16 v[76:79], v[60:63], v[248:251], v[76:79]
	s_waitcnt lgkmcnt(0)
	v_mfma_f32_16x16x32_bf16 v[92:95], v[60:63], v[128:131], v[92:95]
	s_cbranch_vccnz .LBB0_245
	v_cvt_pk_bf16_f32 v80, v202, v203
	v_cvt_pk_bf16_f32 v81, v204, v205
	v_cvt_pk_bf16_f32 v82, v124, v125
	v_cvt_pk_bf16_f32 v83, v126, v127
	ds_read_b64_tr_b16 v[84:85], v163 offset:0
	ds_read_b64_tr_b16 v[86:87], v163 offset:0xb00
	ds_read_b64_tr_b16 v[88:89], v163 offset:32
	ds_read_b64_tr_b16 v[90:91], v163 offset:0xb20
	ds_read_b64_tr_b16 v[60:61], v163 offset:64
	ds_read_b64_tr_b16 v[62:63], v163 offset:0xb40
	ds_read_b64_tr_b16 v[122:123], v163 offset:0x60
	ds_read_b64_tr_b16 v[124:125], v163 offset:0xb60
	s_waitcnt lgkmcnt(0)
	s_nop 1
	v_mfma_f32_16x16x32_bf16 v[84:87], v[80:83], v[84:87], 0
	v_mfma_f32_16x16x32_bf16 v[88:91], v[80:83], v[88:91], 0
	v_mfma_f32_16x16x32_bf16 v[60:63], v[80:83], v[60:63], 0
	v_mfma_f32_16x16x32_bf16 v[80:83], v[80:83], v[122:125], 0
	s_andn2_b64 vcc, exec, s[78:79]
	s_cbranch_vccnz .LBB0_241
